# in-phase syncs after gr_pass (ph5) and after the G1 item loop (ph6) no longer drain outstanding stores (lgkmcnt only)
# baseline (speedup 1.0000x reference)
;     __device__ __forceinline__ bool next(int i, Unit& u) const {
;         const long L = (long)i * G + c; if (L >= nwg) return false;
;         int wgid = (int)L; { const int q = nwg / NXCD, r = nwg % NXCD, xcd = wgid % NXCD, off = wgid / NXCD; wgid = (xcd < r ? xcd * (q + 1) : r * (q + 1) + (xcd - r) * q) + off; }
; __global__ void __launch_bounds__(NT, 2) fwd_kernel(Params P) {
;     ...
;         gr_pass(hbA, (const bf16_t*)(ws + O_WGR), ssq + 2 * M, (float*)(ws + O_GR));
;         __syncthreads();
;         { pg8::Gemm g{hbA, (const bf16_t*)(ws + O_WIN), D, D, D, 0}; pg8::StaticOrder S; S.init(64, 8, G, bx);
;           EpiQKG E{(bf16_t*)(ws + O_Q), (bf16_t*)(ws + O_K), (bf16_t*)(ws + O_G), ssq + 2 * M}; pg8::gemm_phase(ldsl, g, S, E);
.LBB0_1839:
	s_or_b64 exec, exec, s[8:9]
	s_add_u32 s12, s54, 0x2680000
	s_addc_u32 s13, s55, 0
	s_add_u32 s10, s54, 0x614dc00
	s_addc_u32 s11, s55, 0
	v_mov_b32_e32 v8, v210
	s_cmpk_lt_i32 s2, 0x200
	s_waitcnt lgkmcnt(0)
	s_barrier
	s_movk_i32 s8, 0x400
	v_readfirstlane_b32 s3, v8
	s_cselect_b64 s[14:15], -1, 0
	s_cmpk_gt_i32 s2, 0x1ff
	s_cbranch_scc1 .LBB0_1867
	s_ashr_i32 s38, s2, 31
	s_lshr_b32 s6, s38, 29
	s_add_i32 s16, s2, s6
	s_and_b32 s6, s16, -8
	s_sub_i32 s17, s2, s6
	s_cmp_gt_i32 s17, -1
	s_cbranch_scc0 .LBB0_1842
	s_lshl_b32 s9, s17, 6
	s_cbranch_execz .LBB0_1843
	s_branch .LBB0_1844

; __device__ __forceinline__ int defer_tile(int k) { if (k < 1408) return 1472 + k; k -= 1408; if (k < 704) return 3584 + k; k -= 704; if (k < 256) return 4544 + k; k -= 256; if (k < 64) return 4864 + k; k -= 64; return 5696 + k; }
; __device__ __forceinline__ void weight_tile(const Params& P, int t, float* T) {
;     unsigned char* ws = P.ws;
;     {
;         int j = t; const float* src; int ldsrc, nkt, nnt; bf16_t* dst; int ldd; const float* gain = nullptr; int rowmode = 0;
;         if (j < 64) { const int gi = j >> 4; j &= 15; src = P.in[10] + (size_t)gi * 65536; ldsrc = 256; nkt = 4; nnt = 4; dst = (bf16_t*)(ws + O_WP) + (size_t)gi * 65536; ldd = 256; }
;         else if ((j -= 64) < 2816) { const int q = j / 704; j %= 704; const int layer = q >> 1, up = q & 1; src = P.in[up ? 19 : 18] + (size_t)layer * 1024 * 2816; ldsrc = 2816; nkt = 16; nnt = 44;
;             dst = (bf16_t*)(ws + O_WGU) + (size_t)layer * 5632 * 1024; ldd = 1024; gain = P.in[7] + layer * 1024; rowmode = 1 + up; }
;         else if ((j -= 2816) < 1408) { const int layer = j / 704; j %= 704; src = P.in[20] + (size_t)layer * 2816 * 1024; ldsrc = 1024; nkt = 44; nnt = 16; dst = (bf16_t*)(ws + O_WD) + (size_t)layer * 1024 * 2816; ldd = 2816; }
;         else if ((j -= 1408) < 512) { const int layer = j >> 8; j &= 255; src = P.in[22] + (size_t)layer * 1024 * 1024; ldsrc = 1024; nkt = 16; nnt = 16; dst = (bf16_t*)(ws + O_WPG) + (size_t)layer * 1024 * 1024; ldd = 1024; gain = P.in[8] + layer * 1024; }
;         else if ((j -= 512) < 128) { const int layer = j >> 6; j &= 63; src = P.in[21] + (size_t)layer * 256 * 1024; ldsrc = 1024; nkt = 4; nnt = 16; dst = (bf16_t*)(ws + O_WPP) + (size_t)layer * 1024 * 256; ldd = 256; }
;         else if ((j -= 128) < 768) { src = P.in[13]; ldsrc = GIN; nkt = 16; nnt = 48; dst = (bf16_t*)(ws + O_WIN); ldd = 1024; gain = P.in[6] + 1024; rowmode = 3; }
;         else { j -= 768; src = P.in[17]; ldsrc = 1024; nkt = 16; nnt = 16; dst = (bf16_t*)(ws + O_WO); ldd = 1024; }
; __global__ void __launch_bounds__(NT, 2) fwd_kernel(Params P) {
;     ...
;     PHASE(6, gla_g1(P, lds); if (!dup_ && G == 256 && bx >= 64) { __syncthreads(); for (int k = bx - 64; k < N_DEFER; k += 384) weight_tile(P, defer_tile(k), (float*)lds); } )
.LBB0_1978:
	s_cmp_lt_i32 s2, 64
	s_cselect_b64 s[6:7], -1, 0
	s_xor_b64 s[8:9], s[50:51], -1
	s_mov_b64 s[94:95], s[50:51]
	s_or_b64 s[6:7], s[6:7], s[8:9]
	s_mov_b32 s96, s4
	v_readlane_b32 s4, v240, 4
	v_readlane_b32 s50, v240, 2
	s_and_b64 vcc, exec, s[6:7]
	v_readlane_b32 s5, v240, 5
	v_readlane_b32 s51, v240, 3
	s_cbranch_vccnz .LBB0_2019
	s_cmpk_gt_u32 s2, 0xabf
	s_waitcnt lgkmcnt(0)
	s_barrier
	s_cbranch_scc1 .LBB0_2019
	s_load_dwordx2 s[6:7], s[0:1], 0xc0
	s_sub_i32 s3, s2, 64
	s_load_dwordx4 s[8:11], s[0:1], 0x30
	s_load_dwordx2 s[16:17], s[0:1], 0x40
	s_load_dwordx2 s[20:21], s[0:1], 0x88
	s_load_dwordx2 s[22:23], s[0:1], 0x50
	s_load_dwordx2 s[24:25], s[0:1], 0x68
	s_load_dwordx2 s[28:29], s[0:1], 0xb0
	s_load_dwordx4 s[12:15], s[0:1], 0xa0
	s_waitcnt lgkmcnt(0)
	s_add_u32 s18, s6, 0x2c88000
	s_addc_u32 s19, s7, 0
	s_add_u32 s26, s6, 0x2680000
	s_addc_u32 s27, s7, 0
	s_add_u32 s8, s8, 0x1000
	s_addc_u32 s9, s9, 0
	s_add_u32 s46, s6, 0x2580000
	s_addc_u32 s47, s7, 0
	s_add_u32 s48, s6, 0x2180000
	s_addc_u32 s49, s7, 0
	s_add_u32 s60, s6, 0x1680000
	v_lshlrev_b32_e32 v0, 2, v210
	v_lshlrev_b32_e32 v2, 3, v210
	s_addc_u32 s61, s7, 0
	v_lshrrev_b32_e32 v8, 4, v210
	v_and_b32_e32 v0, 60, v0
	v_lshrrev_b32_e32 v9, 3, v210
	v_and_b32_e32 v2, 56, v2
	s_add_u32 s62, s6, 0x80000
	v_mov_b32_e32 v5, 0
	v_lshl_add_u32 v1, v8, 2, 0
	v_mul_u32_u24_e32 v3, 0x104, v0
	v_mul_u32_u24_e32 v4, 0x104, v9
	v_lshlrev_b32_e32 v6, 2, v2
	s_addc_u32 s63, s7, 0
	s_mov_b32 s31, 0
	v_add3_u32 v10, 0, v4, v6
	s_add_i32 s30, s2, 0xfffffe40
	s_movk_i32 s64, 0x9c0
	v_lshlrev_b32_e32 v4, 2, v0
	v_add_u32_e32 v11, v1, v3
	s_movk_i32 s65, 0x800
	s_movk_i32 s76, 0x3ff
	s_movk_i32 s77, 0x3f00
	s_movk_i32 s78, 0x80
	v_lshlrev_b32_e32 v6, 1, v2
	v_mov_b32_e32 v7, v5
	v_mov_b32_e32 v12, 0xfffffc00
	v_mov_b32_e32 v13, 0x400
	s_mov_b32 s32, 0
	s_branch .LBB0_1983
